# top-k phase: static s_setprio 1 for the second wave half (reset at the phase barrier)
# speedup vs baseline: 1.0005x; 1.0005x over previous
; DI int opaque_tid() { int t = threadIdx.x; asm volatile("" : "+v"(t)); return t; }
; DI void topk_select(const float* scores, int* sel, char* smem) {
;   const int tid = opaque_tid();
;   const int lane = tid & 63, w = __builtin_amdgcn_readfirstlane(tid >> 6);
;   unsigned* wsc = (unsigned*)(smem + w * 256);
;   for (int row = blockIdx.x * 8 + w; row < M; row += gridDim.x * 8) {
;     const int t = row % T;
;     const int c = t < 16 ? 0 : 1 + ((t - 16) >> 6);
;     const int nvis = 16 + 64 * c;
;     if (nvis <= 256) continue;
;     unsigned u[33];
;     const float* sr = scores + (size_t)row * SROW;
; #pragma unroll
;     for (int j = 0; j < 33; ++j) {
;       const int idx = lane + 64 * j;
;       u[j] = __float_as_uint(sr[idx < nvis ? idx : nvis - 1]);
;     }
; #pragma unroll
;     for (int j = 0; j < 33; ++j) {
;       const int idx = lane + 64 * j;
;       const unsigned bits = u[j];
;       u[j] = idx < nvis ? ((bits & 0x80000000u) ? ~bits : (bits | 0x80000000u)) : 0u;
.LBB0_573:
	v_readlane_b32 s0, v255, 2
	s_cmp_lt_u32 s0, 33
	s_cbranch_scc1 .LBB0_921
	v_readlane_b32 s4, v254, 60
	v_readlane_b32 s5, v254, 61
	s_add_u32 s26, s4, 0x14fc9000
	s_addc_u32 s27, s5, 0
	s_mov_b64 s[4:5], -1
	s_mov_b64 s[16:17], 0
	s_cmp_lt_i32 s0, 35
	s_mov_b64 s[0:1], 0
	s_cbranch_scc1 .LBB0_819
	v_readlane_b32 s0, v255, 2
	s_cmp_gt_i32 s0, 35
	s_cbranch_scc0 .LBB0_788
	s_cmp_eq_u32 s0, 36
	s_mov_b64 s[0:1], -1
	s_cbranch_scc0 .LBB0_790
	v_mov_b32_e32 v0, v210
	v_readlane_b32 s1, v252, 22
	v_readfirstlane_b32 s0, v0
	s_ashr_i32 s0, s0, 6
	s_add_i32 s18, s0, s1
	s_cmpk_gt_i32 s18, 0x407f
	s_cbranch_scc1 .LBB0_789
	v_and_b32_e32 v2, 63, v0
	s_lshl_b32 s2, s0, 8
	v_lshlrev_b64 v[0:1], v0, -1
	v_not_b32_e32 v1, v1
	v_not_b32_e32 v0, v0
	v_lshl_or_b32 v3, v2, 2, s2
	v_or_b32_e32 v4, 64, v2
	v_or_b32_e32 v5, 0x80, v2
	v_or_b32_e32 v6, 0xc0, v2
	v_or_b32_e32 v7, 0x100, v2
	s_waitcnt vmcnt(19)
	v_or_b32_e32 v8, 0x140, v2
	v_or_b32_e32 v9, 0x180, v2
	v_or_b32_e32 v10, 0x1c0, v2
	v_or_b32_e32 v11, 0x200, v2
	s_waitcnt vmcnt(18)
	v_or_b32_e32 v12, 0x240, v2
	v_or_b32_e32 v13, 0x280, v2
	v_or_b32_e32 v14, 0x2c0, v2
	v_or_b32_e32 v15, 0x300, v2
	s_waitcnt vmcnt(17)
	v_or_b32_e32 v16, 0x340, v2
	v_or_b32_e32 v17, 0x380, v2
	v_or_b32_e32 v18, 0x3c0, v2
	v_or_b32_e32 v19, 0x400, v2
	s_waitcnt vmcnt(16)
	v_or_b32_e32 v20, 0x440, v2
	v_or_b32_e32 v21, 0x480, v2
	v_or_b32_e32 v22, 0x4c0, v2
	v_or_b32_e32 v23, 0x500, v2
	s_waitcnt vmcnt(0)
	v_or_b32_e32 v24, 0x540, v2
	v_or_b32_e32 v25, 0x580, v2
	v_or_b32_e32 v26, 0x5c0, v2
	v_or_b32_e32 v27, 0x600, v2
	v_or_b32_e32 v28, 0x640, v2
	v_or_b32_e32 v29, 0x680, v2
	v_or_b32_e32 v30, 0x6c0, v2
	v_or_b32_e32 v31, 0x700, v2
	v_or_b32_e32 v32, 0x740, v2
	v_or_b32_e32 v33, 0x780, v2
	v_or_b32_e32 v34, 0x7c0, v2
	v_or_b32_e32 v35, 0x800, v2
	v_readfirstlane_b32 vcc_lo, v210
	s_nop 1
	s_cmp_lt_u32 vcc_lo, 0x100
	s_cbranch_scc1 .Ltk_prio_skip
	s_setprio 1
.Ltk_prio_skip:
	s_branch .LBB0_581
.LBB0_579:
	s_or_b64 exec, exec, s[0:1]
